# v110 + counted waits behind the eight row-scale (sum-of-squares) loads of the w_in and ff1 epilogues: each rstd computation waits only for its own word
# speedup vs baseline: 1.0099x; 1.0027x over previous
.LBB0_300:
	v_lshl_add_u32 v156, s24, 8, v3
	v_ashrrev_i32_e32 v157, 31, v156
	v_lshl_add_u64 v[164:165], v[156:157], 3, s[18:19]
	global_load_dwordx2 v[168:169], v[164:165], off
	v_or_b32_e32 v148, 16, v156
	v_ashrrev_i32_e32 v149, 31, v148
	v_lshl_add_u64 v[144:145], v[148:149], 3, s[18:19]
	global_load_dwordx2 v[170:171], v[144:145], off
	v_or_b32_e32 v146, 32, v156
	v_ashrrev_i32_e32 v147, 31, v146
	v_lshl_add_u64 v[144:145], v[146:147], 3, s[18:19]
	global_load_dwordx2 v[172:173], v[144:145], off
	global_load_dwordx2 v[152:153], v[164:165], off offset:1152
	v_or_b32_e32 v144, 48, v156
	v_ashrrev_i32_e32 v145, 31, v144
	v_lshl_add_u64 v[150:151], v[144:145], 3, s[18:19]
	global_load_dwordx2 v[154:155], v[150:151], off
	global_load_dwordx2 v[166:167], v[164:165], off offset:1280
	v_mov_b32_e32 v175, v2
	global_load_dwordx2 v[150:151], v[164:165], off offset:1024
	s_min_u32 s24, s72, 32
	global_load_dwordx2 v[164:165], v[164:165], off offset:1408
	s_sub_i32 s25, 32, s24
	v_add_u32_e32 v157, 0x80, v156
	v_add_u32_e32 v149, 0x90, v156
	v_add_u32_e32 v147, 0xa0, v156
	v_add_u32_e32 v145, 0xb0, v156
	s_mov_b64 s[30:31], -1
	s_cmp_gt_i32 s1, 7
	s_waitcnt vmcnt(7)
	v_mov_b32_e32 v174, v169
	v_lshlrev_b64 v[174:175], s24, v[174:175]
	v_min_u32_e32 v158, 1, v174
	v_or_b32_e32 v158, v175, v158
	v_cvt_f32_u32_e32 v158, v158
	v_cvt_f32_u32_e32 v160, v168
	s_waitcnt vmcnt(6)
	v_mov_b32_e32 v168, v171
	v_mov_b32_e32 v169, v2
	v_ldexp_f32 v158, v158, s25
	v_mul_f32_e32 v158, 0x43800000, v158
	v_fmac_f32_e32 v158, 0x33800000, v160
	v_fmamk_f32 v158, v158, 0x3a000000, v1
	v_lshlrev_b64 v[168:169], s24, v[168:169]
	v_rsq_f32_e32 v162, v158
	v_min_u32_e32 v158, 1, v168
	v_or_b32_e32 v158, v169, v158
	v_cvt_f32_u32_e32 v158, v158
	v_cvt_f32_u32_e32 v160, v170
	s_waitcnt vmcnt(5)
	v_mov_b32_e32 v168, v173
	v_mov_b32_e32 v169, v2
	v_ldexp_f32 v158, v158, s25
	v_mul_f32_e32 v158, 0x43800000, v158
	v_fmac_f32_e32 v158, 0x33800000, v160
	v_fmamk_f32 v158, v158, 0x3a000000, v1
	v_lshlrev_b64 v[168:169], s24, v[168:169]
	v_rsq_f32_e32 v160, v158
	v_min_u32_e32 v158, 1, v168
	v_or_b32_e32 v158, v169, v158
	v_cvt_f32_u32_e32 v158, v158
	v_cvt_f32_u32_e32 v168, v172
	v_mov_b32_e32 v169, v2
	s_waitcnt vmcnt(1)
	v_cvt_f32_u32_e32 v150, v150
	v_ldexp_f32 v158, v158, s25
	v_mul_f32_e32 v158, 0x43800000, v158
	v_fmac_f32_e32 v158, 0x33800000, v168
	v_mov_b32_e32 v168, v155
	v_lshlrev_b64 v[168:169], s24, v[168:169]
	v_min_u32_e32 v155, 1, v168
	v_or_b32_e32 v155, v169, v155
	v_mov_b32_e32 v168, v151
	v_mov_b32_e32 v169, v2
	v_lshlrev_b64 v[168:169], s24, v[168:169]
	v_min_u32_e32 v151, 1, v168
	v_or_b32_e32 v151, v169, v151
	v_cvt_f32_u32_e32 v151, v151
	v_mov_b32_e32 v168, v153
	v_mov_b32_e32 v169, v2
	v_lshlrev_b64 v[168:169], s24, v[168:169]
	v_ldexp_f32 v151, v151, s25
	v_mul_f32_e32 v151, 0x43800000, v151
	v_fmac_f32_e32 v151, 0x33800000, v150
	v_fmamk_f32 v150, v151, 0x3a000000, v1
	v_min_u32_e32 v151, 1, v168
	v_or_b32_e32 v151, v169, v151
	v_cvt_f32_u32_e32 v151, v151
	v_cvt_f32_u32_e32 v152, v152
	v_mov_b32_e32 v168, v167
	v_mov_b32_e32 v169, v2
	v_ldexp_f32 v151, v151, s25
	v_mul_f32_e32 v151, 0x43800000, v151
	v_fmac_f32_e32 v151, 0x33800000, v152
	v_fmamk_f32 v151, v151, 0x3a000000, v1
	v_lshlrev_b64 v[168:169], s24, v[168:169]
	v_rsq_f32_e32 v152, v151
	v_min_u32_e32 v151, 1, v168
	v_or_b32_e32 v151, v169, v151
	v_cvt_f32_u32_e32 v151, v151
	v_cvt_f32_u32_e32 v153, v166
	s_waitcnt vmcnt(0)
	v_mov_b32_e32 v168, v165
	v_mov_b32_e32 v169, v2
	v_ldexp_f32 v151, v151, s25
	v_mul_f32_e32 v151, 0x43800000, v151
	v_fmac_f32_e32 v151, 0x33800000, v153
	v_fmamk_f32 v151, v151, 0x3a000000, v1
	v_lshlrev_b64 v[168:169], s24, v[168:169]
	v_rsq_f32_e32 v166, v151
	v_min_u32_e32 v151, 1, v168
	v_or_b32_e32 v151, v169, v151
	v_cvt_f32_u32_e32 v155, v155
	v_cvt_f32_u32_e32 v151, v151
	v_cvt_f32_u32_e32 v154, v154
	v_cvt_f32_u32_e32 v153, v164
	v_ldexp_f32 v155, v155, s25
	v_ldexp_f32 v151, v151, s25
	v_mul_f32_e32 v155, 0x43800000, v155
	v_mul_f32_e32 v151, 0x43800000, v151
	v_fmac_f32_e32 v155, 0x33800000, v154
	v_fmac_f32_e32 v151, 0x33800000, v153
	v_fmamk_f32 v158, v158, 0x3a000000, v1
	v_fmamk_f32 v154, v155, 0x3a000000, v1
	v_fmamk_f32 v151, v151, 0x3a000000, v1
	v_rsq_f32_e32 v158, v158
	v_rsq_f32_e32 v154, v154
	v_rsq_f32_e32 v150, v150
	v_rsq_f32_e32 v164, v151
	v_lshl_or_b32 v168, s1, 8, v161
	s_cbranch_scc1 .LBB0_303
	s_andn2_b64 vcc, exec, s[30:31]
	s_cbranch_vccz .LBB0_308

.LBB0_339:
	v_lshl_add_u32 v156, s44, 8, v3
	v_ashrrev_i32_e32 v157, 31, v156
	v_lshl_add_u64 v[164:165], v[156:157], 3, s[18:19]
	global_load_dwordx2 v[168:169], v[164:165], off
	v_or_b32_e32 v148, 16, v156
	v_ashrrev_i32_e32 v149, 31, v148
	v_lshl_add_u64 v[144:145], v[148:149], 3, s[18:19]
	global_load_dwordx2 v[170:171], v[144:145], off
	v_or_b32_e32 v146, 32, v156
	v_ashrrev_i32_e32 v147, 31, v146
	v_lshl_add_u64 v[144:145], v[146:147], 3, s[18:19]
	global_load_dwordx2 v[172:173], v[144:145], off
	global_load_dwordx2 v[152:153], v[164:165], off offset:1152
	v_or_b32_e32 v144, 48, v156
	v_ashrrev_i32_e32 v145, 31, v144
	v_lshl_add_u64 v[150:151], v[144:145], 3, s[18:19]
	global_load_dwordx2 v[154:155], v[150:151], off
	global_load_dwordx2 v[166:167], v[164:165], off offset:1280
	v_mov_b32_e32 v175, v2
	global_load_dwordx2 v[150:151], v[164:165], off offset:1024
	s_min_u32 s24, s72, 32
	global_load_dwordx2 v[164:165], v[164:165], off offset:1408
	s_sub_i32 s25, 32, s24
	v_add_u32_e32 v157, 0x80, v156
	v_add_u32_e32 v149, 0x90, v156
	v_add_u32_e32 v147, 0xa0, v156
	v_add_u32_e32 v145, 0xb0, v156
	s_mov_b64 s[30:31], -1
	s_cmp_gt_i32 s1, 7
	s_waitcnt vmcnt(7)
	v_mov_b32_e32 v174, v169
	v_lshlrev_b64 v[174:175], s24, v[174:175]
	v_min_u32_e32 v158, 1, v174
	v_or_b32_e32 v158, v175, v158
	v_cvt_f32_u32_e32 v158, v158
	v_cvt_f32_u32_e32 v160, v168
	s_waitcnt vmcnt(6)
	v_mov_b32_e32 v168, v171
	v_mov_b32_e32 v169, v2
	v_ldexp_f32 v158, v158, s25
	v_mul_f32_e32 v158, 0x43800000, v158
	v_fmac_f32_e32 v158, 0x33800000, v160
	v_fmamk_f32 v158, v158, 0x3a000000, v1
	v_lshlrev_b64 v[168:169], s24, v[168:169]
	v_rsq_f32_e32 v162, v158
	v_min_u32_e32 v158, 1, v168
	v_or_b32_e32 v158, v169, v158
	v_cvt_f32_u32_e32 v158, v158
	v_cvt_f32_u32_e32 v160, v170
	s_waitcnt vmcnt(5)
	v_mov_b32_e32 v168, v173
	v_mov_b32_e32 v169, v2
	v_ldexp_f32 v158, v158, s25
	v_mul_f32_e32 v158, 0x43800000, v158
	v_fmac_f32_e32 v158, 0x33800000, v160
	v_fmamk_f32 v158, v158, 0x3a000000, v1
	v_lshlrev_b64 v[168:169], s24, v[168:169]
	v_rsq_f32_e32 v160, v158
	v_min_u32_e32 v158, 1, v168
	v_or_b32_e32 v158, v169, v158
	v_cvt_f32_u32_e32 v158, v158
	v_cvt_f32_u32_e32 v168, v172
	v_mov_b32_e32 v169, v2
	s_waitcnt vmcnt(1)
	v_cvt_f32_u32_e32 v150, v150
	v_ldexp_f32 v158, v158, s25
	v_mul_f32_e32 v158, 0x43800000, v158
	v_fmac_f32_e32 v158, 0x33800000, v168
	v_mov_b32_e32 v168, v155
	v_lshlrev_b64 v[168:169], s24, v[168:169]
	v_min_u32_e32 v155, 1, v168
	v_or_b32_e32 v155, v169, v155
	v_mov_b32_e32 v168, v151
	v_mov_b32_e32 v169, v2
	v_lshlrev_b64 v[168:169], s24, v[168:169]
	v_min_u32_e32 v151, 1, v168
	v_or_b32_e32 v151, v169, v151
	v_cvt_f32_u32_e32 v151, v151
	v_mov_b32_e32 v168, v153
	v_mov_b32_e32 v169, v2
	v_lshlrev_b64 v[168:169], s24, v[168:169]
	v_ldexp_f32 v151, v151, s25
	v_mul_f32_e32 v151, 0x43800000, v151
	v_fmac_f32_e32 v151, 0x33800000, v150
	v_fmamk_f32 v150, v151, 0x3a000000, v1
	v_min_u32_e32 v151, 1, v168
	v_or_b32_e32 v151, v169, v151
	v_cvt_f32_u32_e32 v151, v151
	v_cvt_f32_u32_e32 v152, v152
	v_mov_b32_e32 v168, v167
	v_mov_b32_e32 v169, v2
	v_ldexp_f32 v151, v151, s25
	v_mul_f32_e32 v151, 0x43800000, v151
	v_fmac_f32_e32 v151, 0x33800000, v152
	v_fmamk_f32 v151, v151, 0x3a000000, v1
	v_lshlrev_b64 v[168:169], s24, v[168:169]
	v_rsq_f32_e32 v152, v151
	v_min_u32_e32 v151, 1, v168
	v_or_b32_e32 v151, v169, v151
	v_cvt_f32_u32_e32 v151, v151
	v_cvt_f32_u32_e32 v153, v166
	s_waitcnt vmcnt(0)
	v_mov_b32_e32 v168, v165
	v_mov_b32_e32 v169, v2
	v_ldexp_f32 v151, v151, s25
	v_mul_f32_e32 v151, 0x43800000, v151
	v_fmac_f32_e32 v151, 0x33800000, v153
	v_fmamk_f32 v151, v151, 0x3a000000, v1
	v_lshlrev_b64 v[168:169], s24, v[168:169]
	v_rsq_f32_e32 v166, v151
	v_min_u32_e32 v151, 1, v168
	v_or_b32_e32 v151, v169, v151
	v_cvt_f32_u32_e32 v155, v155
	v_cvt_f32_u32_e32 v151, v151
	v_cvt_f32_u32_e32 v154, v154
	v_cvt_f32_u32_e32 v153, v164
	v_ldexp_f32 v155, v155, s25
	v_ldexp_f32 v151, v151, s25
	v_mul_f32_e32 v155, 0x43800000, v155
	v_mul_f32_e32 v151, 0x43800000, v151
	v_fmac_f32_e32 v155, 0x33800000, v154
	v_fmac_f32_e32 v151, 0x33800000, v153
	v_fmamk_f32 v158, v158, 0x3a000000, v1
	v_fmamk_f32 v154, v155, 0x3a000000, v1
	v_fmamk_f32 v151, v151, 0x3a000000, v1
	v_rsq_f32_e32 v158, v158
	v_rsq_f32_e32 v154, v154
	v_rsq_f32_e32 v150, v150
	v_rsq_f32_e32 v164, v151
	v_lshl_or_b32 v168, s1, 8, v161
	s_cbranch_scc1 .LBB0_342
	s_andn2_b64 vcc, exec, s[30:31]
	s_cbranch_vccz .LBB0_347

.LBB0_1140:
	v_lshl_add_u32 v150, s63, 8, v3
	v_ashrrev_i32_e32 v151, 31, v150
	v_lshl_add_u64 v[164:165], v[150:151], 3, s[16:17]
	global_load_dwordx2 v[168:169], v[164:165], off
	v_or_b32_e32 v148, 16, v150
	v_ashrrev_i32_e32 v149, 31, v148
	v_lshl_add_u64 v[144:145], v[148:149], 3, s[16:17]
	global_load_dwordx2 v[172:173], v[144:145], off
	v_or_b32_e32 v146, 32, v150
	v_ashrrev_i32_e32 v147, 31, v146
	v_lshl_add_u64 v[144:145], v[146:147], 3, s[16:17]
	global_load_dwordx2 v[174:175], v[144:145], off
	global_load_dwordx2 v[162:163], v[164:165], off offset:1152
	v_or_b32_e32 v144, 48, v150
	v_ashrrev_i32_e32 v145, 31, v144
	v_lshl_add_u64 v[152:153], v[144:145], 3, s[16:17]
	global_load_dwordx2 v[154:155], v[152:153], off
	global_load_dwordx2 v[166:167], v[164:165], off offset:1280
	v_mov_b32_e32 v177, v2
	global_load_dwordx2 v[152:153], v[164:165], off offset:1024
	s_min_u32 s23, s72, 32
	global_load_dwordx2 v[164:165], v[164:165], off offset:1408
	s_sub_i32 s29, 32, s23
	v_add_u32_e32 v170, 0x80, v150
	v_add_u32_e32 v149, 0x90, v150
	v_add_u32_e32 v147, 0xa0, v150
	v_add_u32_e32 v145, 0xb0, v150
	s_andn2_b64 vcc, exec, s[10:11]
	s_waitcnt vmcnt(7)
	v_mov_b32_e32 v176, v169
	v_lshlrev_b64 v[176:177], s23, v[176:177]
	v_min_u32_e32 v151, 1, v176
	v_or_b32_e32 v151, v177, v151
	v_cvt_f32_u32_e32 v151, v151
	v_cvt_f32_u32_e32 v156, v168
	s_waitcnt vmcnt(6)
	v_mov_b32_e32 v168, v173
	v_mov_b32_e32 v169, v2
	v_ldexp_f32 v151, v151, s29
	v_mul_f32_e32 v151, 0x43800000, v151
	v_fmac_f32_e32 v151, 0x33800000, v156
	v_fmamk_f32 v151, v151, 0x3a000000, v1
	v_lshlrev_b64 v[168:169], s23, v[168:169]
	v_rsq_f32_e32 v160, v151
	v_min_u32_e32 v151, 1, v168
	v_or_b32_e32 v151, v169, v151
	v_cvt_f32_u32_e32 v151, v151
	v_cvt_f32_u32_e32 v156, v172
	s_waitcnt vmcnt(5)
	v_mov_b32_e32 v168, v175
	v_mov_b32_e32 v169, v2
	v_ldexp_f32 v151, v151, s29
	v_mul_f32_e32 v151, 0x43800000, v151
	v_fmac_f32_e32 v151, 0x33800000, v156
	v_fmamk_f32 v151, v151, 0x3a000000, v1
	v_lshlrev_b64 v[168:169], s23, v[168:169]
	v_rsq_f32_e32 v158, v151
	v_min_u32_e32 v151, 1, v168
	v_or_b32_e32 v151, v169, v151
	v_cvt_f32_u32_e32 v151, v151
	v_cvt_f32_u32_e32 v156, v174
	s_waitcnt vmcnt(3)
	v_mov_b32_e32 v168, v155
	v_mov_b32_e32 v169, v2
	v_ldexp_f32 v151, v151, s29
	v_mul_f32_e32 v151, 0x43800000, v151
	v_fmac_f32_e32 v151, 0x33800000, v156
	v_fmamk_f32 v151, v151, 0x3a000000, v1
	v_lshlrev_b64 v[168:169], s23, v[168:169]
	v_rsq_f32_e32 v156, v151
	v_min_u32_e32 v151, 1, v168
	v_or_b32_e32 v151, v169, v151
	v_cvt_f32_u32_e32 v151, v151
	v_cvt_f32_u32_e32 v154, v154
	s_waitcnt vmcnt(1)
	v_mov_b32_e32 v168, v153
	v_mov_b32_e32 v169, v2
	v_ldexp_f32 v151, v151, s29
	v_mul_f32_e32 v151, 0x43800000, v151
	v_fmac_f32_e32 v151, 0x33800000, v154
	v_fmamk_f32 v151, v151, 0x3a000000, v1
	v_lshlrev_b64 v[168:169], s23, v[168:169]
	v_rsq_f32_e32 v154, v151
	v_min_u32_e32 v151, 1, v168
	v_or_b32_e32 v151, v169, v151
	v_cvt_f32_u32_e32 v151, v151
	v_cvt_f32_u32_e32 v152, v152
	v_mov_b32_e32 v168, v163
	v_mov_b32_e32 v169, v2
	v_ldexp_f32 v151, v151, s29
	v_mul_f32_e32 v151, 0x43800000, v151
	v_fmac_f32_e32 v151, 0x33800000, v152
	v_fmamk_f32 v151, v151, 0x3a000000, v1
	v_lshlrev_b64 v[168:169], s23, v[168:169]
	v_rsq_f32_e32 v152, v151
	v_min_u32_e32 v151, 1, v168
	v_or_b32_e32 v151, v169, v151
	v_cvt_f32_u32_e32 v151, v151
	v_cvt_f32_u32_e32 v153, v162
	v_mov_b32_e32 v168, v167
	v_mov_b32_e32 v169, v2
	v_ldexp_f32 v151, v151, s29
	v_mul_f32_e32 v151, 0x43800000, v151
	v_fmac_f32_e32 v151, 0x33800000, v153
	v_fmamk_f32 v151, v151, 0x3a000000, v1
	v_lshlrev_b64 v[168:169], s23, v[168:169]
	v_rsq_f32_e32 v162, v151
	v_min_u32_e32 v151, 1, v168
	v_or_b32_e32 v151, v169, v151
	v_cvt_f32_u32_e32 v151, v151
	v_cvt_f32_u32_e32 v153, v166
	s_waitcnt vmcnt(0)
	v_mov_b32_e32 v168, v165
	v_mov_b32_e32 v169, v2
	v_ldexp_f32 v151, v151, s29
	v_mul_f32_e32 v151, 0x43800000, v151
	v_fmac_f32_e32 v151, 0x33800000, v153
	v_fmamk_f32 v151, v151, 0x3a000000, v1
	v_lshlrev_b64 v[168:169], s23, v[168:169]
	v_rsq_f32_e32 v166, v151
	v_min_u32_e32 v151, 1, v168
	v_or_b32_e32 v151, v169, v151
	v_cvt_f32_u32_e32 v151, v151
	v_cvt_f32_u32_e32 v153, v164
	v_pk_mul_f32 v[124:125], v[124:125], v[160:161] op_sel_hi:[1,0]
	v_lshl_or_b32 v172, s62, 8, v159
	v_ldexp_f32 v151, v151, s29
	v_mul_f32_e32 v151, 0x43800000, v151
	v_fmac_f32_e32 v151, 0x33800000, v153
	v_pk_mul_f32 v[128:129], v[128:129], v[160:161] op_sel_hi:[1,0]
	v_pk_mul_f32 v[126:127], v[126:127], v[160:161] op_sel_hi:[1,0]
	v_max_f32_e32 v124, 0, v124
	v_fmamk_f32 v151, v151, 0x3a000000, v1
	v_ashrrev_i32_e32 v173, 31, v172
	v_mov_b64_e32 v[168:169], s[14:15]
	v_pk_mul_f32 v[130:131], v[130:131], v[160:161] op_sel_hi:[1,0]
	v_mul_f32_e32 v153, v124, v124
	v_max_f32_e32 v124, 0, v129
	v_max_f32_e32 v125, 0, v125
	v_max_f32_e32 v126, 0, v126
	v_rsq_f32_e32 v164, v151
	v_mad_i64_i32 v[174:175], s[30:31], v150, s48, v[168:169]
	v_lshlrev_b64 v[150:151], 1, v[172:173]
	v_max_f32_e32 v128, 0, v128
	v_mul_f32_e32 v124, v124, v124
	v_mul_f32_e32 v129, v125, v125
	v_max_f32_e32 v125, 0, v130
	v_mul_f32_e32 v130, v126, v126
	v_max_f32_e32 v126, 0, v131
	v_max_f32_e32 v127, 0, v127
	v_pk_mul_f32 v[118:119], v[118:119], v[160:161] op_sel_hi:[1,0]
	v_pk_mul_f32 v[116:117], v[116:117], v[160:161] op_sel_hi:[1,0]
	v_lshl_add_u64 v[172:173], v[174:175], 0, v[150:151]
	v_mul_f32_e32 v128, v128, v128
	v_mul_f32_e32 v125, v125, v125
	v_mul_f32_e32 v126, v126, v126
	v_mul_f32_e32 v127, v127, v127
	v_cvt_pk_bf16_f32 v124, v128, v124
	v_pk_mul_f32 v[122:123], v[122:123], v[160:161] op_sel_hi:[1,0]
	v_pk_mul_f32 v[120:121], v[120:121], v[160:161] op_sel_hi:[1,0]
	v_max_f32_e32 v116, 0, v116
	v_max_f32_e32 v117, 0, v117
	v_max_f32_e32 v118, 0, v118
	v_cvt_pk_bf16_f32 v125, v125, v126
	v_cvt_pk_bf16_f32 v126, v153, v129
	v_cvt_pk_bf16_f32 v127, v130, v127
	global_store_dwordx4 v[172:173], v[124:127], off
	v_max_f32_e32 v120, 0, v120
	v_max_f32_e32 v119, 0, v119
	v_mul_f32_e32 v124, v116, v116
	v_max_f32_e32 v116, 0, v121
	v_mul_f32_e32 v121, v117, v117
	v_max_f32_e32 v117, 0, v122
	v_mul_f32_e32 v122, v118, v118
	v_max_f32_e32 v118, 0, v123
	v_mul_f32_e32 v116, v116, v116
	v_mul_f32_e32 v117, v117, v117
	v_mul_f32_e32 v118, v118, v118
	v_pk_mul_f32 v[108:109], v[108:109], v[158:159] op_sel_hi:[1,0]
	v_mul_f32_e32 v120, v120, v120
	v_mul_f32_e32 v119, v119, v119
	v_cvt_pk_bf16_f32 v116, v120, v116
	v_cvt_pk_bf16_f32 v117, v117, v118
	v_cvt_pk_bf16_f32 v118, v124, v121
	v_pk_mul_f32 v[112:113], v[112:113], v[158:159] op_sel_hi:[1,0]
	v_pk_mul_f32 v[110:111], v[110:111], v[158:159] op_sel_hi:[1,0]
	v_max_f32_e32 v108, 0, v108
	v_cvt_pk_bf16_f32 v119, v122, v119
	global_store_dwordx4 v[172:173], v[116:119], off offset:256
	v_pk_mul_f32 v[114:115], v[114:115], v[158:159] op_sel_hi:[1,0]
	v_max_f32_e32 v109, 0, v109
	v_mul_f32_e32 v118, v108, v108
	v_max_f32_e32 v108, 0, v113
	v_max_f32_e32 v110, 0, v110
	v_mad_i64_i32 v[116:117], s[30:31], v148, s48, v[168:169]
	v_max_f32_e32 v112, 0, v112
	v_mul_f32_e32 v108, v108, v108
	v_mul_f32_e32 v113, v109, v109
	v_max_f32_e32 v109, 0, v114
	v_mul_f32_e32 v114, v110, v110
	v_max_f32_e32 v110, 0, v115
	v_max_f32_e32 v111, 0, v111
	v_pk_mul_f32 v[102:103], v[102:103], v[158:159] op_sel_hi:[1,0]
	v_pk_mul_f32 v[100:101], v[100:101], v[158:159] op_sel_hi:[1,0]
	v_lshl_add_u64 v[116:117], v[116:117], 0, v[150:151]
	v_mul_f32_e32 v112, v112, v112
	v_mul_f32_e32 v109, v109, v109
	v_mul_f32_e32 v110, v110, v110
	v_mul_f32_e32 v111, v111, v111
	v_cvt_pk_bf16_f32 v108, v112, v108
	v_pk_mul_f32 v[106:107], v[106:107], v[158:159] op_sel_hi:[1,0]
	v_pk_mul_f32 v[104:105], v[104:105], v[158:159] op_sel_hi:[1,0]
	v_max_f32_e32 v100, 0, v100
	v_max_f32_e32 v101, 0, v101
	v_max_f32_e32 v102, 0, v102
	v_cvt_pk_bf16_f32 v109, v109, v110
	v_cvt_pk_bf16_f32 v110, v118, v113
	v_cvt_pk_bf16_f32 v111, v114, v111
	global_store_dwordx4 v[116:117], v[108:111], off
	v_max_f32_e32 v104, 0, v104
	v_max_f32_e32 v103, 0, v103
	v_mul_f32_e32 v108, v100, v100
	v_max_f32_e32 v100, 0, v105
	v_mul_f32_e32 v105, v101, v101
	v_max_f32_e32 v101, 0, v106
	v_mul_f32_e32 v106, v102, v102
	v_max_f32_e32 v102, 0, v107
	v_mul_f32_e32 v100, v100, v100
	v_mul_f32_e32 v101, v101, v101
	v_mul_f32_e32 v102, v102, v102
	v_pk_mul_f32 v[92:93], v[92:93], v[156:157] op_sel_hi:[1,0]
	v_mul_f32_e32 v104, v104, v104
	v_mul_f32_e32 v103, v103, v103
	v_cvt_pk_bf16_f32 v100, v104, v100
	v_cvt_pk_bf16_f32 v101, v101, v102
	v_cvt_pk_bf16_f32 v102, v108, v105
	v_pk_mul_f32 v[96:97], v[96:97], v[156:157] op_sel_hi:[1,0]
	v_pk_mul_f32 v[94:95], v[94:95], v[156:157] op_sel_hi:[1,0]
	v_max_f32_e32 v92, 0, v92
	v_cvt_pk_bf16_f32 v103, v106, v103
	global_store_dwordx4 v[116:117], v[100:103], off offset:256
	v_pk_mul_f32 v[98:99], v[98:99], v[156:157] op_sel_hi:[1,0]
	v_max_f32_e32 v93, 0, v93
	v_mul_f32_e32 v102, v92, v92
	v_max_f32_e32 v92, 0, v97
	v_max_f32_e32 v94, 0, v94
	v_mad_i64_i32 v[100:101], s[30:31], v146, s48, v[168:169]
	v_max_f32_e32 v96, 0, v96
	v_mul_f32_e32 v92, v92, v92
	v_mul_f32_e32 v97, v93, v93
	v_max_f32_e32 v93, 0, v98
	v_mul_f32_e32 v98, v94, v94
	v_max_f32_e32 v94, 0, v99
	v_max_f32_e32 v95, 0, v95
	v_pk_mul_f32 v[86:87], v[86:87], v[156:157] op_sel_hi:[1,0]
	v_pk_mul_f32 v[84:85], v[84:85], v[156:157] op_sel_hi:[1,0]
	v_lshl_add_u64 v[100:101], v[100:101], 0, v[150:151]
	v_mul_f32_e32 v96, v96, v96
	v_mul_f32_e32 v93, v93, v93
	v_mul_f32_e32 v94, v94, v94
	v_mul_f32_e32 v95, v95, v95
	v_cvt_pk_bf16_f32 v92, v96, v92
	v_pk_mul_f32 v[90:91], v[90:91], v[156:157] op_sel_hi:[1,0]
	v_pk_mul_f32 v[88:89], v[88:89], v[156:157] op_sel_hi:[1,0]
	v_max_f32_e32 v84, 0, v84
	v_max_f32_e32 v85, 0, v85
	v_max_f32_e32 v86, 0, v86
	v_cvt_pk_bf16_f32 v93, v93, v94
	v_cvt_pk_bf16_f32 v94, v102, v97
	v_cvt_pk_bf16_f32 v95, v98, v95
	global_store_dwordx4 v[100:101], v[92:95], off
	v_max_f32_e32 v88, 0, v88
	v_max_f32_e32 v87, 0, v87
	v_mul_f32_e32 v92, v84, v84
	v_max_f32_e32 v84, 0, v89
	v_mul_f32_e32 v89, v85, v85
	v_max_f32_e32 v85, 0, v90
	v_mul_f32_e32 v90, v86, v86
	v_max_f32_e32 v86, 0, v91
	v_mul_f32_e32 v84, v84, v84
	v_mul_f32_e32 v85, v85, v85
	v_mul_f32_e32 v86, v86, v86
	v_pk_mul_f32 v[76:77], v[76:77], v[154:155] op_sel_hi:[1,0]
	v_mul_f32_e32 v88, v88, v88
	v_mul_f32_e32 v87, v87, v87
	v_cvt_pk_bf16_f32 v84, v88, v84
	v_cvt_pk_bf16_f32 v85, v85, v86
	v_cvt_pk_bf16_f32 v86, v92, v89
	v_pk_mul_f32 v[80:81], v[80:81], v[154:155] op_sel_hi:[1,0]
	v_pk_mul_f32 v[78:79], v[78:79], v[154:155] op_sel_hi:[1,0]
	v_max_f32_e32 v76, 0, v76
	v_cvt_pk_bf16_f32 v87, v90, v87
	global_store_dwordx4 v[100:101], v[84:87], off offset:256
	v_pk_mul_f32 v[82:83], v[82:83], v[154:155] op_sel_hi:[1,0]
	v_max_f32_e32 v77, 0, v77
	v_mul_f32_e32 v86, v76, v76
	v_max_f32_e32 v76, 0, v81
	v_max_f32_e32 v78, 0, v78
	v_mad_i64_i32 v[84:85], s[30:31], v144, s48, v[168:169]
	v_max_f32_e32 v80, 0, v80
	v_mul_f32_e32 v76, v76, v76
	v_mul_f32_e32 v81, v77, v77
	v_max_f32_e32 v77, 0, v82
	v_mul_f32_e32 v82, v78, v78
	v_max_f32_e32 v78, 0, v83
	v_max_f32_e32 v79, 0, v79
	v_pk_mul_f32 v[70:71], v[70:71], v[154:155] op_sel_hi:[1,0]
	v_pk_mul_f32 v[68:69], v[68:69], v[154:155] op_sel_hi:[1,0]
	v_lshl_add_u64 v[84:85], v[84:85], 0, v[150:151]
	v_mul_f32_e32 v80, v80, v80
	v_mul_f32_e32 v77, v77, v77
	v_mul_f32_e32 v78, v78, v78
	v_mul_f32_e32 v79, v79, v79
	v_cvt_pk_bf16_f32 v76, v80, v76
	v_pk_mul_f32 v[74:75], v[74:75], v[154:155] op_sel_hi:[1,0]
	v_pk_mul_f32 v[72:73], v[72:73], v[154:155] op_sel_hi:[1,0]
	v_max_f32_e32 v68, 0, v68
	v_max_f32_e32 v69, 0, v69
	v_max_f32_e32 v70, 0, v70
	v_cvt_pk_bf16_f32 v77, v77, v78
	v_cvt_pk_bf16_f32 v78, v86, v81
	v_cvt_pk_bf16_f32 v79, v82, v79
	global_store_dwordx4 v[84:85], v[76:79], off
	v_max_f32_e32 v72, 0, v72
	v_max_f32_e32 v71, 0, v71
	v_mul_f32_e32 v76, v68, v68
	v_max_f32_e32 v68, 0, v73
	v_mul_f32_e32 v73, v69, v69
	v_max_f32_e32 v69, 0, v74
	v_mul_f32_e32 v74, v70, v70
	v_max_f32_e32 v70, 0, v75
	v_mul_f32_e32 v68, v68, v68
	v_mul_f32_e32 v69, v69, v69
	v_mul_f32_e32 v70, v70, v70
	v_pk_mul_f32 v[60:61], v[60:61], v[152:153] op_sel_hi:[1,0]
	v_mul_f32_e32 v72, v72, v72
	v_mul_f32_e32 v71, v71, v71
	v_cvt_pk_bf16_f32 v68, v72, v68
	v_cvt_pk_bf16_f32 v69, v69, v70
	v_cvt_pk_bf16_f32 v70, v76, v73
	v_pk_mul_f32 v[64:65], v[64:65], v[152:153] op_sel_hi:[1,0]
	v_pk_mul_f32 v[62:63], v[62:63], v[152:153] op_sel_hi:[1,0]
	v_max_f32_e32 v60, 0, v60
	v_cvt_pk_bf16_f32 v71, v74, v71
	global_store_dwordx4 v[84:85], v[68:71], off offset:256
	v_pk_mul_f32 v[66:67], v[66:67], v[152:153] op_sel_hi:[1,0]
	v_max_f32_e32 v61, 0, v61
	v_mul_f32_e32 v70, v60, v60
	v_max_f32_e32 v60, 0, v65
	v_max_f32_e32 v62, 0, v62
	v_mad_i64_i32 v[68:69], s[30:31], v170, s48, v[168:169]
	v_max_f32_e32 v64, 0, v64
	v_mul_f32_e32 v60, v60, v60
	v_mul_f32_e32 v65, v61, v61
	v_max_f32_e32 v61, 0, v66
	v_mul_f32_e32 v66, v62, v62
	v_max_f32_e32 v62, 0, v67
	v_max_f32_e32 v63, 0, v63
	v_pk_mul_f32 v[54:55], v[54:55], v[152:153] op_sel_hi:[1,0]
	v_pk_mul_f32 v[52:53], v[52:53], v[152:153] op_sel_hi:[1,0]
	v_lshl_add_u64 v[68:69], v[68:69], 0, v[150:151]
	v_mul_f32_e32 v64, v64, v64
	v_mul_f32_e32 v61, v61, v61
	v_mul_f32_e32 v62, v62, v62
	v_mul_f32_e32 v63, v63, v63
	v_cvt_pk_bf16_f32 v60, v64, v60
	v_pk_mul_f32 v[58:59], v[58:59], v[152:153] op_sel_hi:[1,0]
	v_pk_mul_f32 v[56:57], v[56:57], v[152:153] op_sel_hi:[1,0]
	v_max_f32_e32 v52, 0, v52
	v_max_f32_e32 v53, 0, v53
	v_max_f32_e32 v54, 0, v54
	v_cvt_pk_bf16_f32 v61, v61, v62
	v_cvt_pk_bf16_f32 v62, v70, v65
	v_cvt_pk_bf16_f32 v63, v66, v63
	global_store_dwordx4 v[68:69], v[60:63], off
	v_max_f32_e32 v56, 0, v56
	v_max_f32_e32 v55, 0, v55
	v_mul_f32_e32 v60, v52, v52
	v_max_f32_e32 v52, 0, v57
	v_mul_f32_e32 v57, v53, v53
	v_max_f32_e32 v53, 0, v58
	v_mul_f32_e32 v58, v54, v54
	v_max_f32_e32 v54, 0, v59
	v_mul_f32_e32 v52, v52, v52
	v_mul_f32_e32 v53, v53, v53
	v_mul_f32_e32 v54, v54, v54
	v_pk_mul_f32 v[44:45], v[44:45], v[162:163] op_sel_hi:[1,0]
	v_mul_f32_e32 v56, v56, v56
	v_mul_f32_e32 v55, v55, v55
	v_cvt_pk_bf16_f32 v52, v56, v52
	v_cvt_pk_bf16_f32 v53, v53, v54
	v_cvt_pk_bf16_f32 v54, v60, v57
	v_pk_mul_f32 v[48:49], v[48:49], v[162:163] op_sel_hi:[1,0]
	v_pk_mul_f32 v[46:47], v[46:47], v[162:163] op_sel_hi:[1,0]
	v_max_f32_e32 v44, 0, v44
	v_cvt_pk_bf16_f32 v55, v58, v55
	global_store_dwordx4 v[68:69], v[52:55], off offset:256
	v_pk_mul_f32 v[50:51], v[50:51], v[162:163] op_sel_hi:[1,0]
	v_max_f32_e32 v45, 0, v45
	v_mul_f32_e32 v54, v44, v44
	v_max_f32_e32 v44, 0, v49
	v_max_f32_e32 v46, 0, v46
	v_mad_i64_i32 v[52:53], s[30:31], v149, s48, v[168:169]
	v_max_f32_e32 v48, 0, v48
	v_mul_f32_e32 v44, v44, v44
	v_mul_f32_e32 v49, v45, v45
	v_max_f32_e32 v45, 0, v50
	v_mul_f32_e32 v50, v46, v46
	v_max_f32_e32 v46, 0, v51
	v_max_f32_e32 v47, 0, v47
	v_pk_mul_f32 v[38:39], v[38:39], v[162:163] op_sel_hi:[1,0]
	v_pk_mul_f32 v[36:37], v[36:37], v[162:163] op_sel_hi:[1,0]
	v_lshl_add_u64 v[52:53], v[52:53], 0, v[150:151]
	v_mul_f32_e32 v48, v48, v48
	v_mul_f32_e32 v45, v45, v45
	v_mul_f32_e32 v46, v46, v46
	v_mul_f32_e32 v47, v47, v47
	v_cvt_pk_bf16_f32 v44, v48, v44
	v_pk_mul_f32 v[42:43], v[42:43], v[162:163] op_sel_hi:[1,0]
	v_pk_mul_f32 v[40:41], v[40:41], v[162:163] op_sel_hi:[1,0]
	v_max_f32_e32 v36, 0, v36
	v_max_f32_e32 v37, 0, v37
	v_max_f32_e32 v38, 0, v38
	v_cvt_pk_bf16_f32 v45, v45, v46
	v_cvt_pk_bf16_f32 v46, v54, v49
	v_cvt_pk_bf16_f32 v47, v50, v47
	global_store_dwordx4 v[52:53], v[44:47], off
	v_max_f32_e32 v40, 0, v40
	v_max_f32_e32 v39, 0, v39
	v_mul_f32_e32 v44, v36, v36
	v_max_f32_e32 v36, 0, v41
	v_mul_f32_e32 v41, v37, v37
	v_max_f32_e32 v37, 0, v42
	v_mul_f32_e32 v42, v38, v38
	v_max_f32_e32 v38, 0, v43
	v_mul_f32_e32 v36, v36, v36
	v_mul_f32_e32 v37, v37, v37
	v_mul_f32_e32 v38, v38, v38
	v_pk_mul_f32 v[28:29], v[28:29], v[166:167] op_sel_hi:[1,0]
	v_mul_f32_e32 v40, v40, v40
	v_mul_f32_e32 v39, v39, v39
	v_cvt_pk_bf16_f32 v36, v40, v36
	v_cvt_pk_bf16_f32 v37, v37, v38
	v_cvt_pk_bf16_f32 v38, v44, v41
	v_pk_mul_f32 v[32:33], v[32:33], v[166:167] op_sel_hi:[1,0]
	v_pk_mul_f32 v[30:31], v[30:31], v[166:167] op_sel_hi:[1,0]
	v_max_f32_e32 v28, 0, v28
	v_cvt_pk_bf16_f32 v39, v42, v39
	global_store_dwordx4 v[52:53], v[36:39], off offset:256
	v_pk_mul_f32 v[34:35], v[34:35], v[166:167] op_sel_hi:[1,0]
	v_max_f32_e32 v29, 0, v29
	v_mul_f32_e32 v38, v28, v28
	v_max_f32_e32 v28, 0, v33
	v_max_f32_e32 v30, 0, v30
	v_mad_i64_i32 v[36:37], s[30:31], v147, s48, v[168:169]
	v_max_f32_e32 v32, 0, v32
	v_mul_f32_e32 v28, v28, v28
	v_mul_f32_e32 v33, v29, v29
	v_max_f32_e32 v29, 0, v34
	v_mul_f32_e32 v34, v30, v30
	v_max_f32_e32 v30, 0, v35
	v_max_f32_e32 v31, 0, v31
	v_pk_mul_f32 v[22:23], v[22:23], v[166:167] op_sel_hi:[1,0]
	v_pk_mul_f32 v[20:21], v[20:21], v[166:167] op_sel_hi:[1,0]
	v_lshl_add_u64 v[36:37], v[36:37], 0, v[150:151]
	v_mul_f32_e32 v32, v32, v32
	v_mul_f32_e32 v29, v29, v29
	v_mul_f32_e32 v30, v30, v30
	v_mul_f32_e32 v31, v31, v31
	v_cvt_pk_bf16_f32 v28, v32, v28
	v_pk_mul_f32 v[26:27], v[26:27], v[166:167] op_sel_hi:[1,0]
	v_pk_mul_f32 v[24:25], v[24:25], v[166:167] op_sel_hi:[1,0]
	v_max_f32_e32 v20, 0, v20
	v_max_f32_e32 v21, 0, v21
	v_max_f32_e32 v22, 0, v22
	v_cvt_pk_bf16_f32 v29, v29, v30
	v_cvt_pk_bf16_f32 v30, v38, v33
	v_cvt_pk_bf16_f32 v31, v34, v31
	global_store_dwordx4 v[36:37], v[28:31], off
	v_max_f32_e32 v24, 0, v24
	v_max_f32_e32 v23, 0, v23
	v_mul_f32_e32 v28, v20, v20
	v_max_f32_e32 v20, 0, v25
	v_mul_f32_e32 v25, v21, v21
	v_max_f32_e32 v21, 0, v26
	v_mul_f32_e32 v26, v22, v22
	v_max_f32_e32 v22, 0, v27
	v_mul_f32_e32 v20, v20, v20
	v_mul_f32_e32 v21, v21, v21
	v_mul_f32_e32 v22, v22, v22
	v_pk_mul_f32 v[12:13], v[12:13], v[164:165] op_sel_hi:[1,0]
	v_mul_f32_e32 v24, v24, v24
	v_mul_f32_e32 v23, v23, v23
	v_cvt_pk_bf16_f32 v20, v24, v20
	v_cvt_pk_bf16_f32 v21, v21, v22
	v_cvt_pk_bf16_f32 v22, v28, v25
	v_pk_mul_f32 v[16:17], v[16:17], v[164:165] op_sel_hi:[1,0]
	v_pk_mul_f32 v[14:15], v[14:15], v[164:165] op_sel_hi:[1,0]
	v_max_f32_e32 v12, 0, v12
	v_cvt_pk_bf16_f32 v23, v26, v23
	global_store_dwordx4 v[36:37], v[20:23], off offset:256
	v_pk_mul_f32 v[18:19], v[18:19], v[164:165] op_sel_hi:[1,0]
	v_max_f32_e32 v13, 0, v13
	v_mul_f32_e32 v22, v12, v12
	v_max_f32_e32 v12, 0, v17
	v_max_f32_e32 v14, 0, v14
	v_mad_i64_i32 v[20:21], s[30:31], v145, s48, v[168:169]
	v_max_f32_e32 v16, 0, v16
	v_mul_f32_e32 v12, v12, v12
	v_mul_f32_e32 v17, v13, v13
	v_max_f32_e32 v13, 0, v18
	v_mul_f32_e32 v18, v14, v14
	v_max_f32_e32 v14, 0, v19
	v_max_f32_e32 v15, 0, v15
	v_pk_mul_f32 v[6:7], v[6:7], v[164:165] op_sel_hi:[1,0]
	v_pk_mul_f32 v[4:5], v[4:5], v[164:165] op_sel_hi:[1,0]
	v_lshl_add_u64 v[20:21], v[20:21], 0, v[150:151]
	v_mul_f32_e32 v16, v16, v16
	v_mul_f32_e32 v13, v13, v13
	v_mul_f32_e32 v14, v14, v14
	v_mul_f32_e32 v15, v15, v15
	v_cvt_pk_bf16_f32 v12, v16, v12
	v_pk_mul_f32 v[10:11], v[10:11], v[164:165] op_sel_hi:[1,0]
	v_pk_mul_f32 v[8:9], v[8:9], v[164:165] op_sel_hi:[1,0]
	v_max_f32_e32 v4, 0, v4
	v_max_f32_e32 v5, 0, v5
	v_max_f32_e32 v6, 0, v6
	v_cvt_pk_bf16_f32 v13, v13, v14
	v_cvt_pk_bf16_f32 v14, v22, v17
	v_cvt_pk_bf16_f32 v15, v18, v15
	global_store_dwordx4 v[20:21], v[12:15], off
	v_max_f32_e32 v7, 0, v7
	v_max_f32_e32 v8, 0, v8
	v_mul_f32_e32 v12, v4, v4
	v_max_f32_e32 v4, 0, v9
	v_mul_f32_e32 v9, v5, v5
	v_max_f32_e32 v5, 0, v10
	v_mul_f32_e32 v10, v6, v6
	v_max_f32_e32 v6, 0, v11
	v_mul_f32_e32 v4, v4, v4
	v_mul_f32_e32 v5, v5, v5
	v_mul_f32_e32 v6, v6, v6
	v_mul_f32_e32 v7, v7, v7
	s_mov_b64 s[30:31], -1
	v_mul_f32_e32 v8, v8, v8
	v_cvt_pk_bf16_f32 v4, v8, v4
	v_cvt_pk_bf16_f32 v5, v5, v6
	v_cvt_pk_bf16_f32 v6, v12, v9
	v_cvt_pk_bf16_f32 v7, v10, v7
	global_store_dwordx4 v[20:21], v[4:7], off offset:256
	s_cbranch_vccnz .LBB0_1129
	s_andn2_b64 vcc, exec, s[12:13]
	s_cbranch_vccnz .LBB0_1128
	s_barrier
	s_branch .LBB0_1128

.LBB0_1170:
	v_lshl_add_u32 v150, s64, 8, v3
	v_ashrrev_i32_e32 v151, 31, v150
	v_lshl_add_u64 v[164:165], v[150:151], 3, s[16:17]
	global_load_dwordx2 v[168:169], v[164:165], off
	v_or_b32_e32 v148, 16, v150
	v_ashrrev_i32_e32 v149, 31, v148
	v_lshl_add_u64 v[144:145], v[148:149], 3, s[16:17]
	global_load_dwordx2 v[172:173], v[144:145], off
	v_or_b32_e32 v146, 32, v150
	v_ashrrev_i32_e32 v147, 31, v146
	v_lshl_add_u64 v[144:145], v[146:147], 3, s[16:17]
	global_load_dwordx2 v[174:175], v[144:145], off
	global_load_dwordx2 v[162:163], v[164:165], off offset:1152
	v_or_b32_e32 v144, 48, v150
	v_ashrrev_i32_e32 v145, 31, v144
	v_lshl_add_u64 v[152:153], v[144:145], 3, s[16:17]
	global_load_dwordx2 v[154:155], v[152:153], off
	global_load_dwordx2 v[166:167], v[164:165], off offset:1280
	v_mov_b32_e32 v177, v2
	global_load_dwordx2 v[152:153], v[164:165], off offset:1024
	s_min_u32 s29, s72, 32
	global_load_dwordx2 v[164:165], v[164:165], off offset:1408
	s_sub_i32 s30, 32, s29
	v_add_u32_e32 v170, 0x80, v150
	v_add_u32_e32 v149, 0x90, v150
	v_add_u32_e32 v147, 0xa0, v150
	v_add_u32_e32 v145, 0xb0, v150
	s_andn2_b64 vcc, exec, s[22:23]
	s_waitcnt vmcnt(7)
	v_mov_b32_e32 v176, v169
	v_lshlrev_b64 v[176:177], s29, v[176:177]
	v_min_u32_e32 v151, 1, v176
	v_or_b32_e32 v151, v177, v151
	v_cvt_f32_u32_e32 v151, v151
	v_cvt_f32_u32_e32 v156, v168
	s_waitcnt vmcnt(6)
	v_mov_b32_e32 v168, v173
	v_mov_b32_e32 v169, v2
	v_ldexp_f32 v151, v151, s30
	v_mul_f32_e32 v151, 0x43800000, v151
	v_fmac_f32_e32 v151, 0x33800000, v156
	v_fmamk_f32 v151, v151, 0x3a000000, v1
	v_lshlrev_b64 v[168:169], s29, v[168:169]
	v_rsq_f32_e32 v160, v151
	v_min_u32_e32 v151, 1, v168
	v_or_b32_e32 v151, v169, v151
	v_cvt_f32_u32_e32 v151, v151
	v_cvt_f32_u32_e32 v156, v172
	s_waitcnt vmcnt(5)
	v_mov_b32_e32 v168, v175
	v_mov_b32_e32 v169, v2
	v_ldexp_f32 v151, v151, s30
	v_mul_f32_e32 v151, 0x43800000, v151
	v_fmac_f32_e32 v151, 0x33800000, v156
	v_fmamk_f32 v151, v151, 0x3a000000, v1
	v_lshlrev_b64 v[168:169], s29, v[168:169]
	v_rsq_f32_e32 v158, v151
	v_min_u32_e32 v151, 1, v168
	v_or_b32_e32 v151, v169, v151
	v_cvt_f32_u32_e32 v151, v151
	v_cvt_f32_u32_e32 v156, v174
	s_waitcnt vmcnt(3)
	v_mov_b32_e32 v168, v155
	v_mov_b32_e32 v169, v2
	v_ldexp_f32 v151, v151, s30
	v_mul_f32_e32 v151, 0x43800000, v151
	v_fmac_f32_e32 v151, 0x33800000, v156
	v_fmamk_f32 v151, v151, 0x3a000000, v1
	v_lshlrev_b64 v[168:169], s29, v[168:169]
	v_rsq_f32_e32 v156, v151
	v_min_u32_e32 v151, 1, v168
	v_or_b32_e32 v151, v169, v151
	v_cvt_f32_u32_e32 v151, v151
	v_cvt_f32_u32_e32 v154, v154
	s_waitcnt vmcnt(1)
	v_mov_b32_e32 v168, v153
	v_mov_b32_e32 v169, v2
	v_ldexp_f32 v151, v151, s30
	v_mul_f32_e32 v151, 0x43800000, v151
	v_fmac_f32_e32 v151, 0x33800000, v154
	v_fmamk_f32 v151, v151, 0x3a000000, v1
	v_lshlrev_b64 v[168:169], s29, v[168:169]
	v_rsq_f32_e32 v154, v151
	v_min_u32_e32 v151, 1, v168
	v_or_b32_e32 v151, v169, v151
	v_cvt_f32_u32_e32 v151, v151
	v_cvt_f32_u32_e32 v152, v152
	v_mov_b32_e32 v168, v163
	v_mov_b32_e32 v169, v2
	v_ldexp_f32 v151, v151, s30
	v_mul_f32_e32 v151, 0x43800000, v151
	v_fmac_f32_e32 v151, 0x33800000, v152
	v_fmamk_f32 v151, v151, 0x3a000000, v1
	v_lshlrev_b64 v[168:169], s29, v[168:169]
	v_rsq_f32_e32 v152, v151
	v_min_u32_e32 v151, 1, v168
	v_or_b32_e32 v151, v169, v151
	v_cvt_f32_u32_e32 v151, v151
	v_cvt_f32_u32_e32 v153, v162
	v_mov_b32_e32 v168, v167
	v_mov_b32_e32 v169, v2
	v_ldexp_f32 v151, v151, s30
	v_mul_f32_e32 v151, 0x43800000, v151
	v_fmac_f32_e32 v151, 0x33800000, v153
	v_fmamk_f32 v151, v151, 0x3a000000, v1
	v_lshlrev_b64 v[168:169], s29, v[168:169]
	v_rsq_f32_e32 v162, v151
	v_min_u32_e32 v151, 1, v168
	v_or_b32_e32 v151, v169, v151
	v_cvt_f32_u32_e32 v151, v151
	v_cvt_f32_u32_e32 v153, v166
	s_waitcnt vmcnt(0)
	v_mov_b32_e32 v168, v165
	v_mov_b32_e32 v169, v2
	v_ldexp_f32 v151, v151, s30
	v_mul_f32_e32 v151, 0x43800000, v151
	v_fmac_f32_e32 v151, 0x33800000, v153
	v_fmamk_f32 v151, v151, 0x3a000000, v1
	v_lshlrev_b64 v[168:169], s29, v[168:169]
	v_rsq_f32_e32 v166, v151
	v_min_u32_e32 v151, 1, v168
	v_or_b32_e32 v151, v169, v151
	v_cvt_f32_u32_e32 v151, v151
	v_cvt_f32_u32_e32 v153, v164
	v_pk_mul_f32 v[124:125], v[124:125], v[160:161] op_sel_hi:[1,0]
	v_lshl_or_b32 v172, s63, 8, v159
	v_ldexp_f32 v151, v151, s30
	v_mul_f32_e32 v151, 0x43800000, v151
	v_fmac_f32_e32 v151, 0x33800000, v153
	v_pk_mul_f32 v[128:129], v[128:129], v[160:161] op_sel_hi:[1,0]
	v_pk_mul_f32 v[126:127], v[126:127], v[160:161] op_sel_hi:[1,0]
	v_max_f32_e32 v124, 0, v124
	v_fmamk_f32 v151, v151, 0x3a000000, v1
	v_ashrrev_i32_e32 v173, 31, v172
	v_mov_b64_e32 v[168:169], s[14:15]
	v_pk_mul_f32 v[130:131], v[130:131], v[160:161] op_sel_hi:[1,0]
	v_mul_f32_e32 v153, v124, v124
	v_max_f32_e32 v124, 0, v129
	v_max_f32_e32 v125, 0, v125
	v_max_f32_e32 v126, 0, v126
	v_rsq_f32_e32 v164, v151
	v_mad_i64_i32 v[174:175], s[30:31], v150, s48, v[168:169]
	v_lshlrev_b64 v[150:151], 1, v[172:173]
	v_max_f32_e32 v128, 0, v128
	v_mul_f32_e32 v124, v124, v124
	v_mul_f32_e32 v129, v125, v125
	v_max_f32_e32 v125, 0, v130
	v_mul_f32_e32 v130, v126, v126
	v_max_f32_e32 v126, 0, v131
	v_max_f32_e32 v127, 0, v127
	v_pk_mul_f32 v[118:119], v[118:119], v[160:161] op_sel_hi:[1,0]
	v_pk_mul_f32 v[116:117], v[116:117], v[160:161] op_sel_hi:[1,0]
	v_lshl_add_u64 v[172:173], v[174:175], 0, v[150:151]
	v_mul_f32_e32 v128, v128, v128
	v_mul_f32_e32 v125, v125, v125
	v_mul_f32_e32 v126, v126, v126
	v_mul_f32_e32 v127, v127, v127
	v_cvt_pk_bf16_f32 v124, v128, v124
	v_pk_mul_f32 v[122:123], v[122:123], v[160:161] op_sel_hi:[1,0]
	v_pk_mul_f32 v[120:121], v[120:121], v[160:161] op_sel_hi:[1,0]
	v_max_f32_e32 v116, 0, v116
	v_max_f32_e32 v117, 0, v117
	v_max_f32_e32 v118, 0, v118
	v_cvt_pk_bf16_f32 v125, v125, v126
	v_cvt_pk_bf16_f32 v126, v153, v129
	v_cvt_pk_bf16_f32 v127, v130, v127
	global_store_dwordx4 v[172:173], v[124:127], off
	v_max_f32_e32 v120, 0, v120
	v_max_f32_e32 v119, 0, v119
	v_mul_f32_e32 v124, v116, v116
	v_max_f32_e32 v116, 0, v121
	v_mul_f32_e32 v121, v117, v117
	v_max_f32_e32 v117, 0, v122
	v_mul_f32_e32 v122, v118, v118
	v_max_f32_e32 v118, 0, v123
	v_mul_f32_e32 v116, v116, v116
	v_mul_f32_e32 v117, v117, v117
	v_mul_f32_e32 v118, v118, v118
	v_pk_mul_f32 v[108:109], v[108:109], v[158:159] op_sel_hi:[1,0]
	v_mul_f32_e32 v120, v120, v120
	v_mul_f32_e32 v119, v119, v119
	v_cvt_pk_bf16_f32 v116, v120, v116
	v_cvt_pk_bf16_f32 v117, v117, v118
	v_cvt_pk_bf16_f32 v118, v124, v121
	v_pk_mul_f32 v[112:113], v[112:113], v[158:159] op_sel_hi:[1,0]
	v_pk_mul_f32 v[110:111], v[110:111], v[158:159] op_sel_hi:[1,0]
	v_max_f32_e32 v108, 0, v108
	v_cvt_pk_bf16_f32 v119, v122, v119
	global_store_dwordx4 v[172:173], v[116:119], off offset:256
	v_pk_mul_f32 v[114:115], v[114:115], v[158:159] op_sel_hi:[1,0]
	v_max_f32_e32 v109, 0, v109
	v_mul_f32_e32 v118, v108, v108
	v_max_f32_e32 v108, 0, v113
	v_max_f32_e32 v110, 0, v110
	v_mad_i64_i32 v[116:117], s[30:31], v148, s48, v[168:169]
	v_max_f32_e32 v112, 0, v112
	v_mul_f32_e32 v108, v108, v108
	v_mul_f32_e32 v113, v109, v109
	v_max_f32_e32 v109, 0, v114
	v_mul_f32_e32 v114, v110, v110
	v_max_f32_e32 v110, 0, v115
	v_max_f32_e32 v111, 0, v111
	v_pk_mul_f32 v[102:103], v[102:103], v[158:159] op_sel_hi:[1,0]
	v_pk_mul_f32 v[100:101], v[100:101], v[158:159] op_sel_hi:[1,0]
	v_lshl_add_u64 v[116:117], v[116:117], 0, v[150:151]
	v_mul_f32_e32 v112, v112, v112
	v_mul_f32_e32 v109, v109, v109
	v_mul_f32_e32 v110, v110, v110
	v_mul_f32_e32 v111, v111, v111
	v_cvt_pk_bf16_f32 v108, v112, v108
	v_pk_mul_f32 v[106:107], v[106:107], v[158:159] op_sel_hi:[1,0]
	v_pk_mul_f32 v[104:105], v[104:105], v[158:159] op_sel_hi:[1,0]
	v_max_f32_e32 v100, 0, v100
	v_max_f32_e32 v101, 0, v101
	v_max_f32_e32 v102, 0, v102
	v_cvt_pk_bf16_f32 v109, v109, v110
	v_cvt_pk_bf16_f32 v110, v118, v113
	v_cvt_pk_bf16_f32 v111, v114, v111
	global_store_dwordx4 v[116:117], v[108:111], off
	v_max_f32_e32 v104, 0, v104
	v_max_f32_e32 v103, 0, v103
	v_mul_f32_e32 v108, v100, v100
	v_max_f32_e32 v100, 0, v105
	v_mul_f32_e32 v105, v101, v101
	v_max_f32_e32 v101, 0, v106
	v_mul_f32_e32 v106, v102, v102
	v_max_f32_e32 v102, 0, v107
	v_mul_f32_e32 v100, v100, v100
	v_mul_f32_e32 v101, v101, v101
	v_mul_f32_e32 v102, v102, v102
	v_pk_mul_f32 v[92:93], v[92:93], v[156:157] op_sel_hi:[1,0]
	v_mul_f32_e32 v104, v104, v104
	v_mul_f32_e32 v103, v103, v103
	v_cvt_pk_bf16_f32 v100, v104, v100
	v_cvt_pk_bf16_f32 v101, v101, v102
	v_cvt_pk_bf16_f32 v102, v108, v105
	v_pk_mul_f32 v[96:97], v[96:97], v[156:157] op_sel_hi:[1,0]
	v_pk_mul_f32 v[94:95], v[94:95], v[156:157] op_sel_hi:[1,0]
	v_max_f32_e32 v92, 0, v92
	v_cvt_pk_bf16_f32 v103, v106, v103
	global_store_dwordx4 v[116:117], v[100:103], off offset:256
	v_pk_mul_f32 v[98:99], v[98:99], v[156:157] op_sel_hi:[1,0]
	v_max_f32_e32 v93, 0, v93
	v_mul_f32_e32 v102, v92, v92
	v_max_f32_e32 v92, 0, v97
	v_max_f32_e32 v94, 0, v94
	v_mad_i64_i32 v[100:101], s[30:31], v146, s48, v[168:169]
	v_max_f32_e32 v96, 0, v96
	v_mul_f32_e32 v92, v92, v92
	v_mul_f32_e32 v97, v93, v93
	v_max_f32_e32 v93, 0, v98
	v_mul_f32_e32 v98, v94, v94
	v_max_f32_e32 v94, 0, v99
	v_max_f32_e32 v95, 0, v95
	v_pk_mul_f32 v[86:87], v[86:87], v[156:157] op_sel_hi:[1,0]
	v_pk_mul_f32 v[84:85], v[84:85], v[156:157] op_sel_hi:[1,0]
	v_lshl_add_u64 v[100:101], v[100:101], 0, v[150:151]
	v_mul_f32_e32 v96, v96, v96
	v_mul_f32_e32 v93, v93, v93
	v_mul_f32_e32 v94, v94, v94
	v_mul_f32_e32 v95, v95, v95
	v_cvt_pk_bf16_f32 v92, v96, v92
	v_pk_mul_f32 v[90:91], v[90:91], v[156:157] op_sel_hi:[1,0]
	v_pk_mul_f32 v[88:89], v[88:89], v[156:157] op_sel_hi:[1,0]
	v_max_f32_e32 v84, 0, v84
	v_max_f32_e32 v85, 0, v85
	v_max_f32_e32 v86, 0, v86
	v_cvt_pk_bf16_f32 v93, v93, v94
	v_cvt_pk_bf16_f32 v94, v102, v97
	v_cvt_pk_bf16_f32 v95, v98, v95
	global_store_dwordx4 v[100:101], v[92:95], off
	v_max_f32_e32 v88, 0, v88
	v_max_f32_e32 v87, 0, v87
	v_mul_f32_e32 v92, v84, v84
	v_max_f32_e32 v84, 0, v89
	v_mul_f32_e32 v89, v85, v85
	v_max_f32_e32 v85, 0, v90
	v_mul_f32_e32 v90, v86, v86
	v_max_f32_e32 v86, 0, v91
	v_mul_f32_e32 v84, v84, v84
	v_mul_f32_e32 v85, v85, v85
	v_mul_f32_e32 v86, v86, v86
	v_pk_mul_f32 v[76:77], v[76:77], v[154:155] op_sel_hi:[1,0]
	v_mul_f32_e32 v88, v88, v88
	v_mul_f32_e32 v87, v87, v87
	v_cvt_pk_bf16_f32 v84, v88, v84
	v_cvt_pk_bf16_f32 v85, v85, v86
	v_cvt_pk_bf16_f32 v86, v92, v89
	v_pk_mul_f32 v[80:81], v[80:81], v[154:155] op_sel_hi:[1,0]
	v_pk_mul_f32 v[78:79], v[78:79], v[154:155] op_sel_hi:[1,0]
	v_max_f32_e32 v76, 0, v76
	v_cvt_pk_bf16_f32 v87, v90, v87
	global_store_dwordx4 v[100:101], v[84:87], off offset:256
	v_pk_mul_f32 v[82:83], v[82:83], v[154:155] op_sel_hi:[1,0]
	v_max_f32_e32 v77, 0, v77
	v_mul_f32_e32 v86, v76, v76
	v_max_f32_e32 v76, 0, v81
	v_max_f32_e32 v78, 0, v78
	v_mad_i64_i32 v[84:85], s[30:31], v144, s48, v[168:169]
	v_max_f32_e32 v80, 0, v80
	v_mul_f32_e32 v76, v76, v76
	v_mul_f32_e32 v81, v77, v77
	v_max_f32_e32 v77, 0, v82
	v_mul_f32_e32 v82, v78, v78
	v_max_f32_e32 v78, 0, v83
	v_max_f32_e32 v79, 0, v79
	v_pk_mul_f32 v[70:71], v[70:71], v[154:155] op_sel_hi:[1,0]
	v_pk_mul_f32 v[68:69], v[68:69], v[154:155] op_sel_hi:[1,0]
	v_lshl_add_u64 v[84:85], v[84:85], 0, v[150:151]
	v_mul_f32_e32 v80, v80, v80
	v_mul_f32_e32 v77, v77, v77
	v_mul_f32_e32 v78, v78, v78
	v_mul_f32_e32 v79, v79, v79
	v_cvt_pk_bf16_f32 v76, v80, v76
	v_pk_mul_f32 v[74:75], v[74:75], v[154:155] op_sel_hi:[1,0]
	v_pk_mul_f32 v[72:73], v[72:73], v[154:155] op_sel_hi:[1,0]
	v_max_f32_e32 v68, 0, v68
	v_max_f32_e32 v69, 0, v69
	v_max_f32_e32 v70, 0, v70
	v_cvt_pk_bf16_f32 v77, v77, v78
	v_cvt_pk_bf16_f32 v78, v86, v81
	v_cvt_pk_bf16_f32 v79, v82, v79
	global_store_dwordx4 v[84:85], v[76:79], off
	v_max_f32_e32 v72, 0, v72
	v_max_f32_e32 v71, 0, v71
	v_mul_f32_e32 v76, v68, v68
	v_max_f32_e32 v68, 0, v73
	v_mul_f32_e32 v73, v69, v69
	v_max_f32_e32 v69, 0, v74
	v_mul_f32_e32 v74, v70, v70
	v_max_f32_e32 v70, 0, v75
	v_mul_f32_e32 v68, v68, v68
	v_mul_f32_e32 v69, v69, v69
	v_mul_f32_e32 v70, v70, v70
	v_pk_mul_f32 v[60:61], v[60:61], v[152:153] op_sel_hi:[1,0]
	v_mul_f32_e32 v72, v72, v72
	v_mul_f32_e32 v71, v71, v71
	v_cvt_pk_bf16_f32 v68, v72, v68
	v_cvt_pk_bf16_f32 v69, v69, v70
	v_cvt_pk_bf16_f32 v70, v76, v73
	v_pk_mul_f32 v[64:65], v[64:65], v[152:153] op_sel_hi:[1,0]
	v_pk_mul_f32 v[62:63], v[62:63], v[152:153] op_sel_hi:[1,0]
	v_max_f32_e32 v60, 0, v60
	v_cvt_pk_bf16_f32 v71, v74, v71
	global_store_dwordx4 v[84:85], v[68:71], off offset:256
	v_pk_mul_f32 v[66:67], v[66:67], v[152:153] op_sel_hi:[1,0]
	v_max_f32_e32 v61, 0, v61
	v_mul_f32_e32 v70, v60, v60
	v_max_f32_e32 v60, 0, v65
	v_max_f32_e32 v62, 0, v62
	v_mad_i64_i32 v[68:69], s[30:31], v170, s48, v[168:169]
	v_max_f32_e32 v64, 0, v64
	v_mul_f32_e32 v60, v60, v60
	v_mul_f32_e32 v65, v61, v61
	v_max_f32_e32 v61, 0, v66
	v_mul_f32_e32 v66, v62, v62
	v_max_f32_e32 v62, 0, v67
	v_max_f32_e32 v63, 0, v63
	v_pk_mul_f32 v[54:55], v[54:55], v[152:153] op_sel_hi:[1,0]
	v_pk_mul_f32 v[52:53], v[52:53], v[152:153] op_sel_hi:[1,0]
	v_lshl_add_u64 v[68:69], v[68:69], 0, v[150:151]
	v_mul_f32_e32 v64, v64, v64
	v_mul_f32_e32 v61, v61, v61
	v_mul_f32_e32 v62, v62, v62
	v_mul_f32_e32 v63, v63, v63
	v_cvt_pk_bf16_f32 v60, v64, v60
	v_pk_mul_f32 v[58:59], v[58:59], v[152:153] op_sel_hi:[1,0]
	v_pk_mul_f32 v[56:57], v[56:57], v[152:153] op_sel_hi:[1,0]
	v_max_f32_e32 v52, 0, v52
	v_max_f32_e32 v53, 0, v53
	v_max_f32_e32 v54, 0, v54
	v_cvt_pk_bf16_f32 v61, v61, v62
	v_cvt_pk_bf16_f32 v62, v70, v65
	v_cvt_pk_bf16_f32 v63, v66, v63
	global_store_dwordx4 v[68:69], v[60:63], off
	v_max_f32_e32 v56, 0, v56
	v_max_f32_e32 v55, 0, v55
	v_mul_f32_e32 v60, v52, v52
	v_max_f32_e32 v52, 0, v57
	v_mul_f32_e32 v57, v53, v53
	v_max_f32_e32 v53, 0, v58
	v_mul_f32_e32 v58, v54, v54
	v_max_f32_e32 v54, 0, v59
	v_mul_f32_e32 v52, v52, v52
	v_mul_f32_e32 v53, v53, v53
	v_mul_f32_e32 v54, v54, v54
	v_pk_mul_f32 v[44:45], v[44:45], v[162:163] op_sel_hi:[1,0]
	v_mul_f32_e32 v56, v56, v56
	v_mul_f32_e32 v55, v55, v55
	v_cvt_pk_bf16_f32 v52, v56, v52
	v_cvt_pk_bf16_f32 v53, v53, v54
	v_cvt_pk_bf16_f32 v54, v60, v57
	v_pk_mul_f32 v[48:49], v[48:49], v[162:163] op_sel_hi:[1,0]
	v_pk_mul_f32 v[46:47], v[46:47], v[162:163] op_sel_hi:[1,0]
	v_max_f32_e32 v44, 0, v44
	v_cvt_pk_bf16_f32 v55, v58, v55
	global_store_dwordx4 v[68:69], v[52:55], off offset:256
	v_pk_mul_f32 v[50:51], v[50:51], v[162:163] op_sel_hi:[1,0]
	v_max_f32_e32 v45, 0, v45
	v_mul_f32_e32 v54, v44, v44
	v_max_f32_e32 v44, 0, v49
	v_max_f32_e32 v46, 0, v46
	v_mad_i64_i32 v[52:53], s[30:31], v149, s48, v[168:169]
	v_max_f32_e32 v48, 0, v48
	v_mul_f32_e32 v44, v44, v44
	v_mul_f32_e32 v49, v45, v45
	v_max_f32_e32 v45, 0, v50
	v_mul_f32_e32 v50, v46, v46
	v_max_f32_e32 v46, 0, v51
	v_max_f32_e32 v47, 0, v47
	v_pk_mul_f32 v[38:39], v[38:39], v[162:163] op_sel_hi:[1,0]
	v_pk_mul_f32 v[36:37], v[36:37], v[162:163] op_sel_hi:[1,0]
	v_lshl_add_u64 v[52:53], v[52:53], 0, v[150:151]
	v_mul_f32_e32 v48, v48, v48
	v_mul_f32_e32 v45, v45, v45
	v_mul_f32_e32 v46, v46, v46
	v_mul_f32_e32 v47, v47, v47
	v_cvt_pk_bf16_f32 v44, v48, v44
	v_pk_mul_f32 v[42:43], v[42:43], v[162:163] op_sel_hi:[1,0]
	v_pk_mul_f32 v[40:41], v[40:41], v[162:163] op_sel_hi:[1,0]
	v_max_f32_e32 v36, 0, v36
	v_max_f32_e32 v37, 0, v37
	v_max_f32_e32 v38, 0, v38
	v_cvt_pk_bf16_f32 v45, v45, v46
	v_cvt_pk_bf16_f32 v46, v54, v49
	v_cvt_pk_bf16_f32 v47, v50, v47
	global_store_dwordx4 v[52:53], v[44:47], off
	v_max_f32_e32 v40, 0, v40
	v_max_f32_e32 v39, 0, v39
	v_mul_f32_e32 v44, v36, v36
	v_max_f32_e32 v36, 0, v41
	v_mul_f32_e32 v41, v37, v37
	v_max_f32_e32 v37, 0, v42
	v_mul_f32_e32 v42, v38, v38
	v_max_f32_e32 v38, 0, v43
	v_mul_f32_e32 v36, v36, v36
	v_mul_f32_e32 v37, v37, v37
	v_mul_f32_e32 v38, v38, v38
	v_pk_mul_f32 v[28:29], v[28:29], v[166:167] op_sel_hi:[1,0]
	v_mul_f32_e32 v40, v40, v40
	v_mul_f32_e32 v39, v39, v39
	v_cvt_pk_bf16_f32 v36, v40, v36
	v_cvt_pk_bf16_f32 v37, v37, v38
	v_cvt_pk_bf16_f32 v38, v44, v41
	v_pk_mul_f32 v[32:33], v[32:33], v[166:167] op_sel_hi:[1,0]
	v_pk_mul_f32 v[30:31], v[30:31], v[166:167] op_sel_hi:[1,0]
	v_max_f32_e32 v28, 0, v28
	v_cvt_pk_bf16_f32 v39, v42, v39
	global_store_dwordx4 v[52:53], v[36:39], off offset:256
	v_pk_mul_f32 v[34:35], v[34:35], v[166:167] op_sel_hi:[1,0]
	v_max_f32_e32 v29, 0, v29
	v_mul_f32_e32 v38, v28, v28
	v_max_f32_e32 v28, 0, v33
	v_max_f32_e32 v30, 0, v30
	v_mad_i64_i32 v[36:37], s[30:31], v147, s48, v[168:169]
	v_max_f32_e32 v32, 0, v32
	v_mul_f32_e32 v28, v28, v28
	v_mul_f32_e32 v33, v29, v29
	v_max_f32_e32 v29, 0, v34
	v_mul_f32_e32 v34, v30, v30
	v_max_f32_e32 v30, 0, v35
	v_max_f32_e32 v31, 0, v31
	v_pk_mul_f32 v[22:23], v[22:23], v[166:167] op_sel_hi:[1,0]
	v_pk_mul_f32 v[20:21], v[20:21], v[166:167] op_sel_hi:[1,0]
	v_lshl_add_u64 v[36:37], v[36:37], 0, v[150:151]
	v_mul_f32_e32 v32, v32, v32
	v_mul_f32_e32 v29, v29, v29
	v_mul_f32_e32 v30, v30, v30
	v_mul_f32_e32 v31, v31, v31
	v_cvt_pk_bf16_f32 v28, v32, v28
	v_pk_mul_f32 v[26:27], v[26:27], v[166:167] op_sel_hi:[1,0]
	v_pk_mul_f32 v[24:25], v[24:25], v[166:167] op_sel_hi:[1,0]
	v_max_f32_e32 v20, 0, v20
	v_max_f32_e32 v21, 0, v21
	v_max_f32_e32 v22, 0, v22
	v_cvt_pk_bf16_f32 v29, v29, v30
	v_cvt_pk_bf16_f32 v30, v38, v33
	v_cvt_pk_bf16_f32 v31, v34, v31
	global_store_dwordx4 v[36:37], v[28:31], off
	v_max_f32_e32 v24, 0, v24
	v_max_f32_e32 v23, 0, v23
	v_mul_f32_e32 v28, v20, v20
	v_max_f32_e32 v20, 0, v25
	v_mul_f32_e32 v25, v21, v21
	v_max_f32_e32 v21, 0, v26
	v_mul_f32_e32 v26, v22, v22
	v_max_f32_e32 v22, 0, v27
	v_mul_f32_e32 v20, v20, v20
	v_mul_f32_e32 v21, v21, v21
	v_mul_f32_e32 v22, v22, v22
	v_pk_mul_f32 v[12:13], v[12:13], v[164:165] op_sel_hi:[1,0]
	v_mul_f32_e32 v24, v24, v24
	v_mul_f32_e32 v23, v23, v23
	v_cvt_pk_bf16_f32 v20, v24, v20
	v_cvt_pk_bf16_f32 v21, v21, v22
	v_cvt_pk_bf16_f32 v22, v28, v25
	v_pk_mul_f32 v[16:17], v[16:17], v[164:165] op_sel_hi:[1,0]
	v_pk_mul_f32 v[14:15], v[14:15], v[164:165] op_sel_hi:[1,0]
	v_max_f32_e32 v12, 0, v12
	v_cvt_pk_bf16_f32 v23, v26, v23
	global_store_dwordx4 v[36:37], v[20:23], off offset:256
	v_pk_mul_f32 v[18:19], v[18:19], v[164:165] op_sel_hi:[1,0]
	v_max_f32_e32 v13, 0, v13
	v_mul_f32_e32 v22, v12, v12
	v_max_f32_e32 v12, 0, v17
	v_max_f32_e32 v14, 0, v14
	v_mad_i64_i32 v[20:21], s[30:31], v145, s48, v[168:169]
	v_max_f32_e32 v16, 0, v16
	v_mul_f32_e32 v12, v12, v12
	v_mul_f32_e32 v17, v13, v13
	v_max_f32_e32 v13, 0, v18
	v_mul_f32_e32 v18, v14, v14
	v_max_f32_e32 v14, 0, v19
	v_max_f32_e32 v15, 0, v15
	v_pk_mul_f32 v[6:7], v[6:7], v[164:165] op_sel_hi:[1,0]
	v_pk_mul_f32 v[4:5], v[4:5], v[164:165] op_sel_hi:[1,0]
	v_lshl_add_u64 v[20:21], v[20:21], 0, v[150:151]
	v_mul_f32_e32 v16, v16, v16
	v_mul_f32_e32 v13, v13, v13
	v_mul_f32_e32 v14, v14, v14
	v_mul_f32_e32 v15, v15, v15
	v_cvt_pk_bf16_f32 v12, v16, v12
	v_pk_mul_f32 v[10:11], v[10:11], v[164:165] op_sel_hi:[1,0]
	v_pk_mul_f32 v[8:9], v[8:9], v[164:165] op_sel_hi:[1,0]
	v_max_f32_e32 v4, 0, v4
	v_max_f32_e32 v5, 0, v5
	v_max_f32_e32 v6, 0, v6
	v_cvt_pk_bf16_f32 v13, v13, v14
	v_cvt_pk_bf16_f32 v14, v22, v17
	v_cvt_pk_bf16_f32 v15, v18, v15
	global_store_dwordx4 v[20:21], v[12:15], off
	v_max_f32_e32 v7, 0, v7
	v_max_f32_e32 v8, 0, v8
	v_mul_f32_e32 v12, v4, v4
	v_max_f32_e32 v4, 0, v9
	v_mul_f32_e32 v9, v5, v5
	v_max_f32_e32 v5, 0, v10
	v_mul_f32_e32 v10, v6, v6
	v_max_f32_e32 v6, 0, v11
	v_mul_f32_e32 v4, v4, v4
	v_mul_f32_e32 v5, v5, v5
	v_mul_f32_e32 v6, v6, v6
	v_mul_f32_e32 v7, v7, v7
	s_mov_b64 s[30:31], -1
	v_mul_f32_e32 v8, v8, v8
	v_cvt_pk_bf16_f32 v4, v8, v4
	v_cvt_pk_bf16_f32 v5, v5, v6
	v_cvt_pk_bf16_f32 v6, v12, v9
	v_cvt_pk_bf16_f32 v7, v10, v7
	global_store_dwordx4 v[20:21], v[4:7], off offset:256
	s_cbranch_vccnz .LBB0_1159
	s_andn2_b64 vcc, exec, s[10:11]
	s_cbranch_vccnz .LBB0_1158
	s_barrier
	s_branch .LBB0_1158
